# adds: P1b conv-state copy loop unrolled (6 loads in flight, one counted wait, 6 stores) instead of 6 serialised load-wait-store trips
# baseline (speedup 1.0000x reference)
.LBB0_285:
	s_mov_b64 s[10:11], 0x1000
	v_lshl_add_u64 v[18:19], v[4:5], 0, s[10:11]
	v_lshl_add_u64 v[20:21], v[18:19], 0, s[10:11]
	global_load_dword v12, v[4:5], off
	global_load_dword v13, v[4:5], off offset:2048
	global_load_dword v14, v[18:19], off
	global_load_dword v15, v[18:19], off offset:2048
	global_load_dword v16, v[20:21], off
	global_load_dword v17, v[20:21], off offset:2048
	v_ashrrev_i32_e32 v3, 31, v2
	v_lshl_add_u64 v[8:9], v[2:3], 2, s[8:9]
	s_waitcnt vmcnt(5)
	v_lshlrev_b32_e32 v22, 16, v12
	v_and_b32_e32 v23, 0xffff0000, v12
	global_store_dwordx2 v[8:9], v[22:23], off
	v_lshl_add_u64 v[8:9], v[8:9], 0, s[10:11]
	s_waitcnt vmcnt(5)
	v_lshlrev_b32_e32 v24, 16, v13
	v_and_b32_e32 v25, 0xffff0000, v13
	global_store_dwordx2 v[8:9], v[24:25], off
	v_lshl_add_u64 v[8:9], v[8:9], 0, s[10:11]
	s_waitcnt vmcnt(5)
	v_lshlrev_b32_e32 v26, 16, v14
	v_and_b32_e32 v27, 0xffff0000, v14
	global_store_dwordx2 v[8:9], v[26:27], off
	v_lshl_add_u64 v[8:9], v[8:9], 0, s[10:11]
	s_waitcnt vmcnt(5)
	v_lshlrev_b32_e32 v28, 16, v15
	v_and_b32_e32 v29, 0xffff0000, v15
	global_store_dwordx2 v[8:9], v[28:29], off
	v_lshl_add_u64 v[8:9], v[8:9], 0, s[10:11]
	s_waitcnt vmcnt(5)
	v_lshlrev_b32_e32 v30, 16, v16
	v_and_b32_e32 v31, 0xffff0000, v16
	global_store_dwordx2 v[8:9], v[30:31], off
	v_lshl_add_u64 v[8:9], v[8:9], 0, s[10:11]
	s_waitcnt vmcnt(5)
	v_lshlrev_b32_e32 v32, 16, v17
	v_and_b32_e32 v33, 0xffff0000, v17
	global_store_dwordx2 v[8:9], v[32:33], off
	s_branch .LBB0_278
